# scan pass-1 conv taps kept in VGPRs; FFN-out sample-path sgemm unit K-split across workgroup pairs (tagged granule handoff)
# speedup vs baseline: 1.0082x; 1.0082x over previous
.LBB0_1848:
	s_or_b64 exec, exec, s[2:3]
	s_and_b32 s2, s8, 0x3ff
	s_cmp_eq_u32 s11, 0
	s_cselect_b64 s[20:21], -1, 0
	v_cmp_gt_i32_e32 vcc, 0, v50
	s_and_b64 s[28:29], s[20:21], vcc
	v_cmp_gt_i32_e32 vcc, 0, v60
	v_ashrrev_i32_e32 v57, 31, v51
	v_mov_b32_e32 v56, v51
	s_waitcnt vmcnt(10)
	v_cndmask_b32_e64 v37, v37, 0, s[28:29]
	v_cndmask_b32_e64 v36, v36, 0, s[28:29]
	v_cndmask_b32_e64 v35, v35, 0, s[28:29]
	v_cndmask_b32_e64 v34, v34, 0, s[28:29]
	s_and_b64 s[28:29], s[20:21], vcc
	v_cmp_gt_i32_e32 vcc, 0, v61
	v_mul_f32_e32 v50, 0xc1000000, v54
	v_lshlrev_b64 v[56:57], 18, v[56:57]
	s_and_b64 s[20:21], s[20:21], vcc
	v_mul_f32_e32 v118, 0xbfb8aa3b, v52
	v_mul_f32_e32 v120, 0xbfb8aa3b, v53
	v_mul_f32_e32 v144, 0x3fb8aa3b, v50
	v_lshl_add_u64 v[148:149], s[0:1], 0, v[136:137]
	v_mov_b32_e32 v137, 0
	s_mov_b32 s3, 0
	s_waitcnt vmcnt(9)
	v_cndmask_b32_e64 v41, v41, 0, s[28:29]
	v_cndmask_b32_e64 v40, v40, 0, s[28:29]
	v_cndmask_b32_e64 v39, v39, 0, s[28:29]
	v_cndmask_b32_e64 v38, v38, 0, s[28:29]
	s_waitcnt vmcnt(8)
	v_cndmask_b32_e64 v45, v45, 0, s[20:21]
	v_cndmask_b32_e64 v44, v44, 0, s[20:21]
	v_cndmask_b32_e64 v43, v43, 0, s[20:21]
	v_cndmask_b32_e64 v42, v42, 0, s[20:21]
	v_lshl_add_u64 v[142:143], v[134:135], 0, v[56:57]
	v_mov_b32_e32 v119, v118
	v_mov_b32_e32 v121, v120
	v_mov_b32_e32 v145, v144
	v_lshl_add_u64 v[146:147], s[0:1], 0, v[32:33]
	v_lshl_add_u64 v[150:151], s[0:1], 0, v[138:139]
	v_mov_b32_e32 v140, 1.0
	v_mov_b32_e32 v82, 0
	v_mov_b32_e32 v83, v137
	v_mov_b32_e32 v84, v137
	v_mov_b32_e32 v85, v137
	s_waitcnt lgkmcnt(0)
	s_barrier
	v_add_u32_e32 v160, 0x18000, v224
	ds_read_b128 v[188:191], v160 offset:2048
	ds_read_b128 v[192:195], v160 offset:2064
	ds_read_b128 v[196:199], v160
	ds_read_b128 v[200:203], v160 offset:16
	ds_read_b128 v[204:207], v160 offset:512
	ds_read_b128 v[208:211], v160 offset:528
	ds_read_b128 v[236:239], v160 offset:1024
	ds_read_b128 v[240:243], v160 offset:1040
	ds_read_b128 v[244:247], v160 offset:1536
	ds_read_b64 v[212:213], v160 offset:1552
	ds_read_b64 v[248:249], v160 offset:1560
	s_waitcnt lgkmcnt(0)

.LBB0_1854:
	v_cndmask_b32_e64 v139, 0, 1, s[48:49]
	v_cmp_ne_u32_e32 vcc, 1, v139
	v_add_u32_e32 v139, s1, v223
	v_lshl_add_u32 v158, v139, 8, v126
	ds_read_b128 v[176:179], v158
	ds_read_b128 v[168:171], v158 offset:256
	ds_read_b128 v[172:175], v158 offset:512
	v_ashrrev_i32_e32 v139, 2, v139
	v_and_b32_e32 v139, -4, v139
	v_add_u32_e32 v139, v139, v225
	s_mov_b32 s1, 32
	s_mov_b64 s[48:49], 0
	s_and_b64 vcc, exec, vcc
	s_waitcnt lgkmcnt(2)
	v_lshlrev_b32_e32 v186, 16, v176
	v_and_b32_e32 v187, 0xffff0000, v176
	v_pk_fma_f32 v[152:153], v[196:197], v[186:187], v[188:189]
	v_lshlrev_b32_e32 v186, 16, v177
	v_and_b32_e32 v187, 0xffff0000, v177
	v_pk_fma_f32 v[180:181], v[198:199], v[186:187], v[190:191]
	v_lshlrev_b32_e32 v186, 16, v178
	v_and_b32_e32 v187, 0xffff0000, v178
	v_pk_fma_f32 v[182:183], v[200:201], v[186:187], v[192:193]
	v_lshlrev_b32_e32 v186, 16, v179
	v_and_b32_e32 v187, 0xffff0000, v179
	v_pk_fma_f32 v[184:185], v[202:203], v[186:187], v[194:195]
	ds_read_b128 v[176:179], v158 offset:768
	s_waitcnt lgkmcnt(2)
	v_lshlrev_b32_e32 v186, 16, v168
	v_and_b32_e32 v187, 0xffff0000, v168
	v_pk_fma_f32 v[152:153], v[204:205], v[186:187], v[152:153]
	v_lshlrev_b32_e32 v186, 16, v169
	v_and_b32_e32 v187, 0xffff0000, v169
	v_pk_fma_f32 v[180:181], v[206:207], v[186:187], v[180:181]
	v_lshlrev_b32_e32 v186, 16, v170
	v_and_b32_e32 v187, 0xffff0000, v170
	v_pk_fma_f32 v[182:183], v[208:209], v[186:187], v[182:183]
	v_lshlrev_b32_e32 v186, 16, v171
	v_and_b32_e32 v187, 0xffff0000, v171
	v_pk_fma_f32 v[184:185], v[210:211], v[186:187], v[184:185]
	s_waitcnt lgkmcnt(1)
	v_lshlrev_b32_e32 v186, 16, v172
	v_and_b32_e32 v187, 0xffff0000, v172
	v_pk_fma_f32 v[152:153], v[236:237], v[186:187], v[152:153]
	v_lshlrev_b32_e32 v186, 16, v173
	v_and_b32_e32 v187, 0xffff0000, v173
	v_pk_fma_f32 v[180:181], v[238:239], v[186:187], v[180:181]
	v_lshlrev_b32_e32 v186, 16, v174
	v_and_b32_e32 v187, 0xffff0000, v174
	v_pk_fma_f32 v[182:183], v[240:241], v[186:187], v[182:183]
	v_lshlrev_b32_e32 v186, 16, v175
	v_and_b32_e32 v187, 0xffff0000, v175
	v_pk_fma_f32 v[184:185], v[242:243], v[186:187], v[184:185]
	s_waitcnt lgkmcnt(0)
	v_lshlrev_b32_e32 v186, 16, v176
	v_and_b32_e32 v187, 0xffff0000, v176
	v_pk_fma_f32 v[172:173], v[244:245], v[186:187], v[152:153]
	v_lshlrev_b32_e32 v186, 16, v177
	v_and_b32_e32 v187, 0xffff0000, v177
	v_pk_fma_f32 v[174:175], v[246:247], v[186:187], v[180:181]
	v_lshlrev_b32_e32 v186, 16, v178
	v_and_b32_e32 v187, 0xffff0000, v178
	v_pk_fma_f32 v[168:169], v[212:213], v[186:187], v[182:183]
	v_lshlrev_b32_e32 v186, 16, v179
	v_and_b32_e32 v187, 0xffff0000, v179
	v_pk_fma_f32 v[170:171], v[248:249], v[186:187], v[184:185]
	v_mad_u64_u32 v[152:153], s[20:21], v139, s10, v[126:127]
	v_cvt_pk_bf16_f32 v176, v172, v173
	v_cvt_pk_bf16_f32 v177, v174, v175
	v_cvt_pk_bf16_f32 v178, v168, v169
	v_cvt_pk_bf16_f32 v179, v170, v171
	ds_write_b128 v152, v[176:179] offset:33792
	v_mad_u64_u32 v[152:153], s[20:21], v139, s33, v[128:129]
	ds_write_b128 v152, v[172:175] offset:51200
	ds_write_b128 v152, v[168:171] offset:51216
	s_cbranch_vccz .LBB0_1854
	s_waitcnt vmcnt(12)
	v_pk_add_f32 v[82:83], v[110:111], v[82:83]
	v_pk_add_f32 v[84:85], v[112:113], v[84:85]
	v_pk_add_f32 v[82:83], v[86:87], v[82:83]
	s_waitcnt lgkmcnt(0)
	s_barrier
	v_add_u32_e32 v110, v226, v233
	v_pk_add_f32 v[84:85], v[88:89], v[84:85]
	v_pk_add_f32 v[82:83], v[90:91], v[82:83]
	ds_read_b128 v[88:91], v110 offset:33792
	v_pk_add_f32 v[84:85], v[92:93], v[84:85]
	v_pk_add_f32 v[82:83], v[94:95], v[82:83]
	v_pk_add_f32 v[84:85], v[96:97], v[84:85]
	v_pk_add_f32 v[82:83], v[98:99], v[82:83]
	ds_read_b128 v[96:99], v110 offset:33856
	s_waitcnt lgkmcnt(1)
	v_mfma_f32_16x16x32_bf16 v[92:95], v[88:91], v[0:3], 0
	v_add_f32_e64 v84, v100, v84
	v_add_f32_e64 v85, v101, v85
	v_pk_add_f32 v[86:87], v[102:103], v[82:83]
	v_pk_add_f32 v[84:85], v[104:105], v[84:85]
	v_mfma_f32_16x16x32_bf16 v[88:91], v[88:91], v[8:11], 0
	ds_read_b128 v[102:105], v110 offset:38208
	ds_read_b128 v[168:171], v110 offset:42560
	v_pk_add_f32 v[82:83], v[108:109], v[84:85]
	s_waitcnt lgkmcnt(2)
	v_mfma_f32_16x16x32_bf16 v[92:95], v[96:99], v[4:7], v[92:95]
	v_add_f32_e64 v86, v106, v86
	v_add_f32_e64 v87, v107, v87
	s_cmp_eq_u32 s0, 8
	ds_read_b128 v[176:179], v110 offset:46912
	v_mfma_f32_16x16x32_bf16 v[88:91], v[96:99], v[12:15], v[88:91]
	ds_read_b128 v[96:99], v110 offset:33920
	s_waitcnt lgkmcnt(0)
	v_mfma_f32_16x16x32_bf16 v[92:95], v[96:99], v[16:19], v[92:95]
	v_mfma_f32_16x16x32_bf16 v[88:91], v[96:99], v[24:27], v[88:91]
	ds_read_b128 v[96:99], v110 offset:33984
	s_waitcnt lgkmcnt(0)
	v_mfma_f32_16x16x32_bf16 v[92:95], v[96:99], v[20:23], v[92:95]
	s_nop 7
	v_pk_fma_f32 v[84:85], v[92:93], s[26:27], v[118:119] op_sel_hi:[1,0,1] neg_lo:[1,0,0] neg_hi:[1,0,0]
	s_nop 0
	v_exp_f32_e32 v84, v84
	v_exp_f32_e32 v85, v85
	v_mfma_f32_16x16x32_bf16 v[88:91], v[96:99], v[28:31], v[88:91]
	v_fma_f32 v94, -v94, s26, v118
	v_fma_f32 v95, -v95, s26, v119
	ds_read2_b32 v[96:97], v235 offset1:132
	v_pk_add_f32 v[84:85], v[84:85], 1.0 op_sel_hi:[1,0]
	v_exp_f32_e32 v94, v94
	v_rcp_f32_e32 v84, v84
	v_rcp_f32_e32 v85, v85
	s_nop 0
	v_pk_fma_f32 v[88:89], v[88:89], s[26:27], v[120:121] op_sel_hi:[1,0,1] neg_lo:[1,0,0] neg_hi:[1,0,0]
	v_exp_f32_e32 v95, v95
	v_exp_f32_e32 v88, v88
	v_exp_f32_e32 v89, v89
	v_pk_mul_f32 v[84:85], v[144:145], v[84:85]
	v_pk_fma_f32 v[90:91], v[90:91], s[26:27], v[120:121] op_sel_hi:[1,0,1] neg_lo:[1,0,0] neg_hi:[1,0,0]
	v_exp_f32_e32 v84, v84
	v_exp_f32_e32 v85, v85
	v_pk_add_f32 v[88:89], v[88:89], 1.0 op_sel_hi:[1,0]
	v_pk_add_f32 v[94:95], v[94:95], 1.0 op_sel_hi:[1,0]
	v_exp_f32_e32 v90, v90
	v_exp_f32_e32 v91, v91
	v_rcp_f32_e32 v88, v88
	v_rcp_f32_e32 v89, v89
	v_rcp_f32_e32 v94, v94
	v_rcp_f32_e32 v95, v95
	v_pk_fma_f32 v[92:93], v[84:85], v[84:85], 1.0 op_sel_hi:[1,1,0] neg_lo:[1,0,0] neg_hi:[1,0,0]
	v_pk_add_f32 v[90:91], v[90:91], 1.0 op_sel_hi:[1,0]
	v_max_f32 v92, v92, 0
	v_max_f32 v93, v93, 0
	s_waitcnt lgkmcnt(0)
	v_pk_mul_f32 v[88:89], v[96:97], v[88:89]
	v_sqrt_f32_e32 v92, v92
	v_sqrt_f32_e32 v93, v93
	v_rcp_f32_e32 v96, v90
	v_rcp_f32_e32 v97, v91
	v_pk_mul_f32 v[90:91], v[144:145], v[94:95]
	v_pk_mul_f32 v[88:89], v[92:93], v[88:89]
	v_exp_f32_e32 v90, v90
	v_exp_f32_e32 v91, v91
	v_add_u32_e32 v92, 0xcc00, v234
	ds_read2_b32 v[92:93], v92 offset0:8 offset1:140
	v_fma_f32 v88, 0, v84, v88
	v_pk_fma_f32 v[94:95], v[90:91], v[90:91], 1.0 op_sel_hi:[1,1,0] neg_lo:[1,0,0] neg_hi:[1,0,0]
	v_fmac_f32_e32 v89, v85, v88
	v_max_f32 v94, v94, 0
	v_max_f32 v95, v95, 0
	s_waitcnt lgkmcnt(0)
	v_pk_mul_f32 v[92:93], v[92:93], v[96:97]
	v_sqrt_f32_e32 v94, v94
	v_sqrt_f32_e32 v95, v95
	v_mul_f32_e32 v84, v84, v85
	v_mul_f32_e32 v84, v90, v84
	v_mul_f32_e32 v84, v91, v84
	v_pk_mul_f32 v[92:93], v[94:95], v[92:93]
	ds_read_b128 v[94:97], v110 offset:38144
	s_waitcnt lgkmcnt(0)
	v_mfma_f32_16x16x32_bf16 v[98:101], v[94:97], v[0:3], 0
	v_fma_f32 v85, v90, v89, v92
	v_fmac_f32_e32 v93, v91, v85
	v_mfma_f32_16x16x32_bf16 v[94:97], v[94:97], v[8:11], 0
	v_mfma_f32_16x16x32_bf16 v[98:101], v[102:105], v[4:7], v[98:101]
	v_mfma_f32_16x16x32_bf16 v[94:97], v[102:105], v[12:15], v[94:97]
	ds_read_b128 v[102:105], v110 offset:38272
	s_waitcnt lgkmcnt(0)
	v_mfma_f32_16x16x32_bf16 v[98:101], v[102:105], v[16:19], v[98:101]
	v_mfma_f32_16x16x32_bf16 v[94:97], v[102:105], v[24:27], v[94:97]
	ds_read_b128 v[102:105], v110 offset:38336
	s_waitcnt lgkmcnt(0)
	v_mfma_f32_16x16x32_bf16 v[98:101], v[102:105], v[20:23], v[98:101]
	v_mfma_f32_16x16x32_bf16 v[102:105], v[102:105], v[28:31], v[94:97]
	s_nop 3
	v_add_u32_e32 v94, 0xe800, v234
	ds_read2_b32 v[96:97], v94 offset0:64 offset1:196
	s_nop 0
	v_pk_fma_f32 v[94:95], v[98:99], s[26:27], v[118:119] op_sel_hi:[1,0,1] neg_lo:[1,0,0] neg_hi:[1,0,0]
	v_pk_fma_f32 v[98:99], v[102:103], s[26:27], v[120:121] op_sel_hi:[1,0,1] neg_lo:[1,0,0] neg_hi:[1,0,0]
	v_exp_f32_e32 v94, v94
	v_exp_f32_e32 v95, v95
	v_exp_f32_e32 v98, v98
	v_exp_f32_e32 v99, v99
	v_pk_add_f32 v[94:95], v[94:95], 1.0 op_sel_hi:[1,0]
	s_nop 0
	v_rcp_f32_e32 v94, v94
	v_rcp_f32_e32 v95, v95
	v_pk_add_f32 v[98:99], v[98:99], 1.0 op_sel_hi:[1,0]
	v_pk_mul_f32 v[94:95], v[144:145], v[94:95]
	s_nop 0
	v_exp_f32_e32 v94, v94
	v_exp_f32_e32 v95, v95
	v_rcp_f32_e32 v98, v98
	v_rcp_f32_e32 v99, v99
	v_mul_f32_e32 v84, v84, v94
	v_pk_fma_f32 v[102:103], v[94:95], v[94:95], 1.0 op_sel_hi:[1,1,0] neg_lo:[1,0,0] neg_hi:[1,0,0]
	v_mul_f32_e32 v84, v95, v84
	v_max_f32 v102, v102, 0
	v_max_f32 v103, v103, 0
	s_waitcnt lgkmcnt(0)
	v_pk_mul_f32 v[96:97], v[96:97], v[98:99]
	v_sqrt_f32_e32 v102, v102
	v_sqrt_f32_e32 v103, v103
	v_add_u32_e32 v98, 0xec00, v234
	v_pk_mul_f32 v[96:97], v[102:103], v[96:97]
	ds_read2_b32 v[102:103], v98 offset0:72 offset1:204
	v_pk_fma_f32 v[98:99], v[100:101], s[26:27], v[118:119] op_sel_hi:[1,0,1] neg_lo:[1,0,0] neg_hi:[1,0,0]
	v_pk_fma_f32 v[100:101], v[104:105], s[26:27], v[120:121] op_sel_hi:[1,0,1] neg_lo:[1,0,0] neg_hi:[1,0,0]
	v_exp_f32_e32 v98, v98
	v_exp_f32_e32 v99, v99
	v_exp_f32_e32 v100, v100
	v_exp_f32_e32 v101, v101
	v_fma_f32 v85, v93, v94, v96
	v_pk_add_f32 v[98:99], v[98:99], 1.0 op_sel_hi:[1,0]
	v_fmac_f32_e32 v97, v95, v85
	v_rcp_f32_e32 v98, v98
	v_rcp_f32_e32 v99, v99
	v_pk_add_f32 v[100:101], v[100:101], 1.0 op_sel_hi:[1,0]
	v_pk_mul_f32 v[98:99], v[144:145], v[98:99]
	s_nop 0
	v_exp_f32_e32 v98, v98
	v_exp_f32_e32 v99, v99
	v_rcp_f32_e32 v100, v100
	v_rcp_f32_e32 v101, v101
	v_mul_f32_e32 v84, v98, v84
	v_pk_fma_f32 v[104:105], v[98:99], v[98:99], 1.0 op_sel_hi:[1,1,0] neg_lo:[1,0,0] neg_hi:[1,0,0]
	v_mul_f32_e32 v84, v99, v84
	v_max_f32 v104, v104, 0
	v_max_f32 v105, v105, 0
	s_waitcnt lgkmcnt(0)
	v_pk_mul_f32 v[100:101], v[102:103], v[100:101]
	v_sqrt_f32_e32 v104, v104
	v_sqrt_f32_e32 v105, v105
	s_nop 0
	v_pk_mul_f32 v[100:101], v[104:105], v[100:101]
	ds_read_b128 v[102:105], v110 offset:42496
	s_waitcnt lgkmcnt(0)
	v_mfma_f32_16x16x32_bf16 v[106:109], v[102:105], v[0:3], 0
	v_fma_f32 v85, v98, v97, v100
	v_fmac_f32_e32 v101, v99, v85
	v_mfma_f32_16x16x32_bf16 v[102:105], v[102:105], v[8:11], 0
	v_mfma_f32_16x16x32_bf16 v[106:109], v[168:171], v[4:7], v[106:109]
	v_mfma_f32_16x16x32_bf16 v[102:105], v[168:171], v[12:15], v[102:105]
	ds_read_b128 v[168:171], v110 offset:42624
	s_waitcnt lgkmcnt(0)
	v_mfma_f32_16x16x32_bf16 v[106:109], v[168:171], v[16:19], v[106:109]
	v_mfma_f32_16x16x32_bf16 v[102:105], v[168:171], v[24:27], v[102:105]
	ds_read_b128 v[168:171], v110 offset:42688
	s_waitcnt lgkmcnt(0)
	v_mfma_f32_16x16x32_bf16 v[106:109], v[168:171], v[20:23], v[106:109]
	v_mfma_f32_16x16x32_bf16 v[168:171], v[168:171], v[28:31], v[102:105]
	s_nop 3
	v_add_u32_e32 v102, 0x4200, v235
	ds_read2_b32 v[104:105], v102 offset1:132
	s_nop 0
	v_pk_fma_f32 v[102:103], v[106:107], s[26:27], v[118:119] op_sel_hi:[1,0,1] neg_lo:[1,0,0] neg_hi:[1,0,0]
	v_pk_fma_f32 v[106:107], v[168:169], s[26:27], v[120:121] op_sel_hi:[1,0,1] neg_lo:[1,0,0] neg_hi:[1,0,0]
	v_exp_f32_e32 v102, v102
	v_exp_f32_e32 v103, v103
	v_exp_f32_e32 v106, v106
	v_exp_f32_e32 v107, v107
	v_pk_add_f32 v[102:103], v[102:103], 1.0 op_sel_hi:[1,0]
	s_nop 0
	v_rcp_f32_e32 v102, v102
	v_rcp_f32_e32 v103, v103
	v_pk_add_f32 v[106:107], v[106:107], 1.0 op_sel_hi:[1,0]
	v_pk_mul_f32 v[102:103], v[144:145], v[102:103]
	s_nop 0
	v_exp_f32_e32 v102, v102
	v_exp_f32_e32 v103, v103
	v_rcp_f32_e32 v106, v106
	v_rcp_f32_e32 v107, v107
	v_mul_f32_e32 v84, v84, v102
	v_pk_fma_f32 v[112:113], v[102:103], v[102:103], 1.0 op_sel_hi:[1,1,0] neg_lo:[1,0,0] neg_hi:[1,0,0]
	v_mul_f32_e32 v84, v103, v84
	v_max_f32 v113, v113, 0
	v_max_f32 v111, v112, 0
	s_waitcnt lgkmcnt(0)
	v_pk_mul_f32 v[104:105], v[104:105], v[106:107]
	v_sqrt_f32_e32 v112, v111
	v_sqrt_f32_e32 v113, v113
	v_add_u32_e32 v106, 0x4600, v235
	v_pk_mul_f32 v[104:105], v[112:113], v[104:105]
	ds_read2_b32 v[112:113], v106 offset0:8 offset1:140
	v_pk_fma_f32 v[106:107], v[108:109], s[26:27], v[118:119] op_sel_hi:[1,0,1] neg_lo:[1,0,0] neg_hi:[1,0,0]
	v_pk_fma_f32 v[108:109], v[170:171], s[26:27], v[120:121] op_sel_hi:[1,0,1] neg_lo:[1,0,0] neg_hi:[1,0,0]
	ds_read_b128 v[168:171], v110 offset:46848
	v_exp_f32_e32 v106, v106
	v_exp_f32_e32 v107, v107
	v_exp_f32_e32 v108, v108
	v_exp_f32_e32 v109, v109
	s_waitcnt lgkmcnt(0)
	v_mfma_f32_16x16x32_bf16 v[172:175], v[168:171], v[0:3], 0
	v_add_f32_e64 v106, v106, 1.0
	v_add_f32_e64 v107, v107, 1.0
	v_pk_add_f32 v[108:109], v[108:109], 1.0 op_sel_hi:[1,0]
	v_rcp_f32_e32 v106, v106
	v_rcp_f32_e32 v107, v107
	v_mfma_f32_16x16x32_bf16 v[168:171], v[168:171], v[8:11], 0
	v_rcp_f32_e32 v108, v108
	v_rcp_f32_e32 v109, v109
	v_pk_mul_f32 v[106:107], v[144:145], v[106:107]
	v_mfma_f32_16x16x32_bf16 v[172:175], v[176:179], v[4:7], v[172:175]
	v_exp_f32_e32 v106, v106
	v_exp_f32_e32 v107, v107
	v_pk_mul_f32 v[108:109], v[112:113], v[108:109]
	v_mfma_f32_16x16x32_bf16 v[168:171], v[176:179], v[12:15], v[168:171]
	ds_read_b128 v[176:179], v110 offset:46976
	v_pk_fma_f32 v[152:153], v[106:107], v[106:107], 1.0 op_sel_hi:[1,1,0] neg_lo:[1,0,0] neg_hi:[1,0,0]
	v_fma_f32 v85, v101, v102, v104
	v_max_f32 v111, v152, 0
	s_waitcnt lgkmcnt(0)
	v_mfma_f32_16x16x32_bf16 v[172:175], v[176:179], v[16:19], v[172:175]
	v_sqrt_f32_e32 v152, v111
	ds_read_b128 v[110:113], v110 offset:47040
	v_max_f32 v139, v153, 0
	v_mfma_f32_16x16x32_bf16 v[168:171], v[176:179], v[24:27], v[168:171]
	v_sqrt_f32_e32 v153, v139
	v_add_u32_e32 v139, 0x6200, v235
	v_fmac_f32_e32 v105, v103, v85
	s_waitcnt lgkmcnt(0)
	v_mfma_f32_16x16x32_bf16 v[172:175], v[110:113], v[20:23], v[172:175]
	v_mul_f32_e64 v108, v152, v108
	v_mul_f32_e64 v109, v153, v109
	ds_read2_b32 v[152:153], v139 offset0:64 offset1:196
	v_fma_f32 v85, v106, v105, v108
	v_mfma_f32_16x16x32_bf16 v[110:113], v[110:113], v[28:31], v[168:171]
	v_mul_f32_e32 v84, v106, v84
	v_fmac_f32_e32 v109, v107, v85
	v_mul_f32_e32 v84, v107, v84
	v_pk_fma_f32 v[168:169], v[172:173], s[26:27], v[118:119] op_sel_hi:[1,0,1] neg_lo:[1,0,0] neg_hi:[1,0,0]
	s_nop 0
	v_exp_f32_e32 v168, v168
	v_exp_f32_e32 v169, v169
	s_nop 0
	v_pk_fma_f32 v[110:111], v[110:111], s[26:27], v[120:121] op_sel_hi:[1,0,1] neg_lo:[1,0,0] neg_hi:[1,0,0]
	v_pk_fma_f32 v[112:113], v[112:113], s[26:27], v[120:121] op_sel_hi:[1,0,1] neg_lo:[1,0,0] neg_hi:[1,0,0]
	v_exp_f32_e32 v110, v110
	v_pk_add_f32 v[168:169], v[168:169], 1.0 op_sel_hi:[1,0]
	v_exp_f32_e32 v111, v111
	v_rcp_f32_e32 v168, v168
	v_rcp_f32_e32 v169, v169
	v_exp_f32_e32 v112, v112
	v_pk_add_f32 v[110:111], v[110:111], 1.0 op_sel_hi:[1,0]
	v_exp_f32_e32 v113, v113
	v_pk_mul_f32 v[168:169], v[144:145], v[168:169]
	v_rcp_f32_e32 v110, v110
	v_exp_f32_e32 v168, v168
	v_exp_f32_e32 v169, v169
	v_rcp_f32_e32 v111, v111
	v_pk_add_f32 v[112:113], v[112:113], 1.0 op_sel_hi:[1,0]
	v_mul_f32_e32 v84, v84, v168
	v_pk_fma_f32 v[170:171], v[168:169], v[168:169], 1.0 op_sel_hi:[1,1,0] neg_lo:[1,0,0] neg_hi:[1,0,0]
	s_waitcnt lgkmcnt(0)
	v_pk_mul_f32 v[110:111], v[152:153], v[110:111]
	v_max_f32 v139, v170, 0
	v_max_f32 v141, v171, 0
	v_rcp_f32_e32 v112, v112
	v_sqrt_f32_e32 v170, v139
	v_sqrt_f32_e32 v171, v141
	v_add_u32_e32 v139, 0x6600, v235
	ds_read2_b32 v[152:153], v139 offset0:72 offset1:204
	v_rcp_f32_e32 v113, v113
	v_pk_mul_f32 v[110:111], v[170:171], v[110:111]
	v_pk_fma_f32 v[170:171], v[174:175], s[26:27], v[118:119] op_sel_hi:[1,0,1] neg_lo:[1,0,0] neg_hi:[1,0,0]
	v_fma_f32 v85, v109, v168, v110
	v_exp_f32_e32 v170, v170
	v_exp_f32_e32 v171, v171
	s_waitcnt lgkmcnt(0)
	v_pk_mul_f32 v[112:113], v[152:153], v[112:113]
	v_fmac_f32_e32 v111, v169, v85
	v_mul_f32_e32 v84, v169, v84
	v_pk_add_f32 v[170:171], v[170:171], 1.0 op_sel_hi:[1,0]
	s_nop 0
	v_rcp_f32_e32 v170, v170
	v_rcp_f32_e32 v171, v171
	s_nop 0
	v_pk_mul_f32 v[170:171], v[144:145], v[170:171]
	s_nop 0
	v_exp_f32_e32 v170, v170
	v_exp_f32_e32 v171, v171
	v_mul_f32_e32 v84, v170, v84
	v_pk_fma_f32 v[172:173], v[170:171], v[170:171], 1.0 op_sel_hi:[1,1,0] neg_lo:[1,0,0] neg_hi:[1,0,0]
	v_mul_f32_e32 v88, v171, v84
	v_max_f32 v139, v172, 0
	v_max_f32 v141, v173, 0
	s_nop 0
	v_sqrt_f32_e32 v172, v139
	v_sqrt_f32_e32 v173, v141
	s_nop 0
	v_pk_mul_f32 v[112:113], v[172:173], v[112:113]
	s_nop 0
	v_fma_f32 v85, v170, v111, v112
	v_fmac_f32_e32 v113, v171, v85
	s_waitcnt vmcnt(11)
	v_pk_add_f32 v[84:85], v[48:49], v[82:83]
	v_pk_add_f32 v[82:83], v[46:47], v[86:87]
	v_add_u32_e32 v46, -16, v216
	v_and_b32_e32 v47, 64, v216
	v_cmp_lt_i32_e32 vcc, v46, v47
	v_subrev_u32_e32 v49, 32, v216
	s_nop 0
	v_cndmask_b32_e32 v46, v46, v216, vcc
	v_lshlrev_b32_e32 v46, 2, v46
	ds_bpermute_b32 v48, v46, v88
	ds_bpermute_b32 v46, v46, v113
	v_cmp_lt_i32_e32 vcc, v49, v47
	v_or_b32_e32 v47, v47, v127
	v_lshlrev_b32_e32 v47, 2, v47
	s_waitcnt lgkmcnt(1)
	v_mul_f32_e32 v48, v88, v48
	s_waitcnt lgkmcnt(0)
	v_fma_f32 v46, v88, v46, v113
	v_cndmask_b32_e32 v49, v49, v216, vcc
	v_cndmask_b32_e64 v48, v48, v88, s[36:37]
	v_cndmask_b32_e64 v46, v46, v113, s[36:37]
	v_lshlrev_b32_e32 v49, 2, v49
	ds_bpermute_b32 v86, v49, v48
	ds_bpermute_b32 v49, v49, v46
	s_waitcnt lgkmcnt(1)
	v_mul_f32_e32 v86, v48, v86
	s_waitcnt lgkmcnt(0)
	v_fma_f32 v49, v48, v49, v46
	v_cndmask_b32_e64 v48, v48, v86, s[38:39]
	v_cndmask_b32_e64 v46, v46, v49, s[38:39]
	ds_bpermute_b32 v48, v47, v48 offset:192
	ds_bpermute_b32 v152, v47, v46 offset:192
	s_waitcnt lgkmcnt(1)
	v_mul_f32_e32 v140, v140, v48
	s_waitcnt lgkmcnt(0)
	v_fmac_f32_e32 v152, v137, v48
	s_cbranch_scc1 .LBB0_1859
	s_waitcnt vmcnt(7)
	v_mov_b64_e32 v[112:113], v[52:53]
	s_waitcnt vmcnt(6)
	v_mov_b64_e32 v[88:89], v[56:57]
	s_waitcnt vmcnt(5)
	v_mov_b64_e32 v[92:93], v[60:61]
	s_waitcnt vmcnt(4)
	v_mov_b64_e32 v[96:97], v[64:65]
	s_waitcnt vmcnt(3)
	v_mov_b64_e32 v[100:101], v[68:69]
	s_waitcnt vmcnt(2)
	v_mov_b64_e32 v[104:105], v[72:73]
	s_waitcnt vmcnt(1)
	v_mov_b64_e32 v[108:109], v[76:77]
	s_waitcnt vmcnt(0)
	v_mov_b64_e32 v[46:47], v[78:79]
	v_mov_b64_e32 v[110:111], v[50:51]
	v_mov_b64_e32 v[86:87], v[54:55]
	v_mov_b64_e32 v[90:91], v[58:59]
	v_mov_b64_e32 v[94:95], v[62:63]
	v_mov_b64_e32 v[98:99], v[66:67]
	v_mov_b64_e32 v[102:103], v[70:71]
	v_mov_b64_e32 v[106:107], v[74:75]
	v_mov_b64_e32 v[48:49], v[80:81]
	v_mov_b32_e32 v137, v152
	s_mov_b32 s3, s0
	s_branch .LBB0_1849

.LBB0_2746:
	s_and_b64 vcc, exec, s[2:3]
	s_cbranch_vccz .LBB0_2881
	v_lshlrev_b32_e32 v0, 4, v56
	v_add_u32_e32 v1, 0x2000, v0
	v_ashrrev_i32_e32 v2, 31, v1
	v_lshrrev_b32_e32 v2, 22, v2
	v_add_u32_e32 v2, v1, v2
	v_ashrrev_i32_e32 v71, 10, v2
	v_mul_i32_i24_e32 v2, 0x400, v71
	v_sub_u32_e32 v1, v1, v2
	v_lshrrev_b32_e32 v2, 4, v1
	v_bitop3_b32 v1, v2, v1, 32 bitop3:0x6c
	v_ashrrev_i32_e32 v2, 31, v1
	v_lshrrev_b32_e32 v2, 26, v2
	v_add_u32_e32 v2, v1, v2
	v_lshlrev_b32_e32 v3, 3, v71
	v_ashrrev_i32_e32 v72, 6, v2
	v_and_b32_e32 v3, -16, v3
	v_add_u32_e32 v3, v72, v3
	v_and_b32_e32 v4, 3, v72
	s_mov_b32 s3, 0xffffe0
	v_lshrrev_b32_e32 v5, 2, v3
	v_lshlrev_b32_e32 v6, 1, v3
	v_and_b32_e32 v2, 0xc0, v2
	v_writelane_b32 v255, s40, 10
	v_and_or_b32 v4, v3, s3, v4
	v_and_b32_e32 v5, 4, v5
	v_and_b32_e32 v6, 24, v6
	v_sub_u32_e32 v1, v1, v2
	v_readlane_b32 s2, v255, 7
	v_or3_b32 v4, v4, v5, v6
	v_lshlrev_b32_e32 v5, 5, v71
	v_ashrrev_i16_sdwa v1, v215, sext(v1) dst_sel:DWORD dst_unused:UNUSED_PAD src0_sel:DWORD src1_sel:BYTE_0
	s_ashr_i32 s95, s2, 6
	v_and_b32_e32 v73, 32, v5
	v_bfe_i32 v74, v1, 0, 16
	s_movk_i32 s2, 0xb00
	v_mul_u32_u24_e32 v4, 0xb00, v4
	v_add_u32_e32 v1, v73, v74
	v_mul_lo_u32 v2, v3, s2
	v_add_lshl_u32 v170, v4, v1, 1
	v_add_lshl_u32 v172, v1, v2, 1
	v_bfe_i32 v1, v56, 27, 1
	v_lshrrev_b32_e32 v1, 22, v1
	v_add_u32_e32 v1, v0, v1
	v_and_b32_e32 v1, 0xfffffc00, v1
	v_sub_u32_e32 v0, v0, v1
	v_lshrrev_b32_e32 v1, 4, v0
	v_ashrrev_i32_e32 v2, 31, v56
	v_bitop3_b32 v0, v1, v0, 32 bitop3:0x6c
	v_lshrrev_b32_e32 v2, 26, v2
	v_ashrrev_i32_e32 v1, 31, v0
	v_add_u32_e32 v2, v56, v2
	v_lshrrev_b32_e32 v1, 26, v1
	v_ashrrev_i32_e32 v76, 6, v2
	v_add_u32_e32 v1, v0, v1
	v_lshlrev_b32_e32 v2, 3, v76
	v_ashrrev_i32_e32 v75, 6, v1
	v_and_b32_e32 v2, -16, v2
	v_add_u32_e32 v2, v75, v2
	v_and_b32_e32 v3, 3, v75
	v_lshrrev_b32_e32 v4, 2, v2
	v_lshlrev_b32_e32 v5, 1, v2
	v_and_b32_e32 v1, 0xc0, v1
	v_and_or_b32 v3, v2, s3, v3
	v_and_b32_e32 v4, 4, v4
	v_and_b32_e32 v5, 24, v5
	v_sub_u32_e32 v0, v0, v1
	s_lshl_b32 s17, s95, 10
	v_or3_b32 v3, v3, v4, v5
	v_lshlrev_b32_e32 v4, 5, v76
	v_ashrrev_i16_sdwa v0, v215, sext(v0) dst_sel:DWORD dst_unused:UNUSED_PAD src0_sel:DWORD src1_sel:BYTE_0
	v_mul_lo_u32 v1, v2, s2
	v_readlane_b32 s2, v254, 19
	v_and_b32_e32 v77, 32, v4
	v_bfe_i32 v78, v0, 0, 16
	s_add_u32 s60, s77, s2
	v_readlane_b32 s2, v254, 17
	v_mul_u32_u24_e32 v3, 0xb00, v3
	v_add_u32_e32 v0, v77, v78
	s_addc_u32 s61, s78, s2
	s_add_i32 s30, s17, 0
	v_add_lshl_u32 v174, v3, v0, 1
	s_add_i32 m0, s30, 0x10000
	v_add_lshl_u32 v176, v0, v1, 1
	global_load_lds_dwordx4 v174, s[60:61]
	s_add_i32 m0, s30, 0x12000
	s_add_u32 s2, s60, 0xb0000
	global_load_lds_dwordx4 v170, s[60:61]
	s_addc_u32 s3, s61, 0
	s_add_i32 m0, s30, 0x14000
	v_writelane_b32 v255, s37, 14
	global_load_lds_dwordx4 v174, s[2:3]
	s_add_i32 m0, s30, 0x16000
	s_nop 0
	global_load_lds_dwordx4 v170, s[2:3]
	v_readlane_b32 s2, v254, 16
	s_add_u32 s58, s75, s2
	v_readlane_b32 s2, v254, 13
	s_addc_u32 s59, s76, s2
	s_add_i32 s31, s30, 0x2000
	s_mov_b32 m0, s30
	s_add_u32 s2, s58, 0xb0000
	global_load_lds_dwordx4 v176, s[58:59]
	s_mov_b32 m0, s31
	s_addc_u32 s3, s59, 0
	s_add_i32 s79, s30, 0x4000
	global_load_lds_dwordx4 v172, s[58:59]
	s_mov_b32 m0, s79
	s_add_i32 s80, s30, 0x6000
	global_load_lds_dwordx4 v176, s[2:3]
	s_mov_b32 m0, s80
	s_abs_i32 s8, s74
	global_load_lds_dwordx4 v172, s[2:3]
	v_cvt_f32_u32_e32 v0, s8
	s_sub_i32 s20, 0, s8
	s_abs_i32 s3, s37
	s_ashr_i32 s2, s37, 31
	v_rcp_iflag_f32_e32 v0, v0
	s_nop 0
	v_mul_f32_e32 v0, 0x4f7ffffe, v0
	v_cvt_u32_f32_e32 v0, v0
	s_nop 0
	v_readfirstlane_b32 s28, v0
	s_mul_i32 s20, s20, s28
	s_mul_hi_u32 s20, s28, s20
	s_add_i32 s28, s28, s20
	s_mul_hi_u32 s20, s3, s28
	s_mul_i32 s20, s20, s8
	s_sub_i32 s3, s3, s20
	s_sub_i32 s20, s3, s8
	s_cmp_ge_u32 s3, s8
	s_cselect_b32 s3, s20, s3
	s_sub_i32 s20, s3, s8
	s_cmp_ge_u32 s3, s8
	s_cselect_b32 s3, s20, s3
	s_xor_b32 s3, s3, s2
	s_sub_i32 s29, s3, s2
	s_mov_b32 s100, 0
	s_mov_b32 s101, 0
	s_cmp_gt_i32 s29, 31
	s_cbranch_scc0 .LBB0_2755
	s_cmp_gt_i32 s29, 63
	s_cbranch_scc1 .LBB0_2748
	s_sub_i32 s29, s29, 32
	s_movk_i32 s100, 0x160
	s_branch .LBB0_2755

.LBB0_2755:
	v_lshl_add_u64 v[248:249], v[162:163], 0, s[100:101]
	v_lshl_or_b32 v24, s29, 5, v201
	s_movk_i32 s2, 0x1600
	v_mad_i64_i32 v[30:31], s[2:3], v24, s2, v[164:165]
	v_lshl_add_u64 v[30:31], v[30:31], 0, s[100:101]
	global_load_dwordx4 v[48:51], v[248:249], off
	global_load_dwordx4 v[52:55], v[30:31], off
	global_load_dwordx4 v[80:83], v[248:249], off offset:32
	global_load_dwordx4 v[84:87], v[30:31], off offset:32
	global_load_dwordx4 v[88:91], v[248:249], off offset:64
	global_load_dwordx4 v[92:95], v[30:31], off offset:64
	global_load_dwordx4 v[96:99], v[248:249], off offset:96
	global_load_dwordx4 v[100:103], v[30:31], off offset:96
	global_load_dwordx4 v[104:107], v[248:249], off offset:128
	global_load_dwordx4 v[108:111], v[30:31], off offset:128
	global_load_dwordx4 v[112:115], v[248:249], off offset:160
	global_load_dwordx4 v[116:119], v[30:31], off offset:160
	global_load_dwordx4 v[120:123], v[248:249], off offset:192
	global_load_dwordx4 v[124:127], v[30:31], off offset:192
	global_load_dwordx4 v[128:131], v[248:249], off offset:224
	global_load_dwordx4 v[132:135], v[30:31], off offset:224
	global_load_dwordx4 v[136:139], v[248:249], off offset:256
	global_load_dwordx4 v[140:143], v[30:31], off offset:256
	global_load_dwordx4 v[144:147], v[248:249], off offset:288
	global_load_dwordx4 v[148:151], v[30:31], off offset:288
	global_load_dwordx4 v[180:183], v[248:249], off offset:320
	global_load_dwordx4 v[184:187], v[30:31], off offset:320
	v_add_u32_e32 v30, 0x8c00, v204
	v_add_u32_e32 v26, v24, v202
	v_add_u32_e32 v28, 0x4000, v26
	v_ashrrev_i32_e32 v27, 31, v26
	v_ashrrev_i32_e32 v29, 31, v28
	v_lshl_add_u64 v[26:27], v[26:27], 2, s[92:93]
	v_lshl_add_u64 v[28:29], v[28:29], 2, s[92:93]
	global_load_dword v26, v[26:27], off
	s_nop 0
	global_load_dword v25, v[28:29], off
	v_add_u32_e32 v27, 0x8000, v204
	v_add_u32_e32 v28, 0x8400, v204
	v_add_u32_e32 v29, 0x8800, v204
	s_waitcnt vmcnt(22)
	v_mfma_f32_32x32x16_bf16 v[0:15], v[48:51], v[52:55], 0
	s_waitcnt vmcnt(20)
	v_mfma_f32_32x32x16_bf16 v[0:15], v[80:83], v[84:87], v[0:15]
	s_waitcnt vmcnt(18)
	v_mfma_f32_32x32x16_bf16 v[0:15], v[88:91], v[92:95], v[0:15]
	s_waitcnt vmcnt(16)
	v_mfma_f32_32x32x16_bf16 v[0:15], v[96:99], v[100:103], v[0:15]
	s_waitcnt vmcnt(14)
	v_mfma_f32_32x32x16_bf16 v[0:15], v[104:107], v[108:111], v[0:15]
	s_waitcnt vmcnt(12)
	v_mfma_f32_32x32x16_bf16 v[0:15], v[112:115], v[116:119], v[0:15]
	s_waitcnt vmcnt(10)
	v_mfma_f32_32x32x16_bf16 v[0:15], v[120:123], v[124:127], v[0:15]
	s_waitcnt vmcnt(8)
	v_mfma_f32_32x32x16_bf16 v[0:15], v[128:131], v[132:135], v[0:15]
	s_waitcnt vmcnt(6)
	v_mfma_f32_32x32x16_bf16 v[0:15], v[136:139], v[140:143], v[0:15]
	s_waitcnt vmcnt(4)
	v_mfma_f32_32x32x16_bf16 v[0:15], v[144:147], v[148:151], v[0:15]
	s_waitcnt vmcnt(2)
	v_mfma_f32_32x32x16_bf16 v[0:15], v[180:183], v[184:187], v[0:15]
	s_waitcnt vmcnt(0)
	s_nop 11
	ds_write2_b32 v27, v0, v1 offset1:32
	ds_write2_b32 v27, v2, v3 offset0:64 offset1:96
	ds_write2_b32 v28, v4, v5 offset1:32
	ds_write2_b32 v28, v6, v7 offset0:64 offset1:96
	ds_write2_b32 v29, v8, v9 offset1:32
	ds_write2_b32 v29, v10, v11 offset0:64 offset1:96
	ds_write2_b32 v30, v12, v13 offset1:32
	ds_write2_b32 v30, v14, v15 offset0:64 offset1:96
	s_waitcnt lgkmcnt(0)
	s_barrier
	s_and_saveexec_b64 s[38:39], s[34:35]
	s_movk_i32 s20, 0x1ff
	s_movk_i32 s36, 0x1080
	s_cbranch_execz .LBB0_2758
	s_mov_b64 s[2:3], 0
	v_mov_b32_e32 v0, v200

.LBB0_2758:
	s_or_b64 exec, exec, s[38:39]
	s_waitcnt lgkmcnt(0)
	s_barrier
	s_sub_u32 s38, s92, 0x24ac0000
	s_subb_u32 s39, s93, 0
	v_lshlrev_b32_e32 v34, 4, v200
	v_lshl_add_u32 v34, s29, 13, v34
	v_mov_b32_e32 v35, 0
	v_lshl_add_u64 v[34:35], v[34:35], 0, s[38:39]
	v_readlane_b32 s38, v254, 49
	s_nop 3
	s_add_i32 s38, s38, 1
	s_cmp_lg_u32 s100, 0
	s_cbranch_scc1 .Lsp_hi
	s_mov_b32 s39, 0
.Lsp_poll:
	global_load_dwordx2 v[36:37], v[34:35], off sc1
	global_load_dwordx2 v[38:39], v[34:35], off offset:8 sc1
	s_waitcnt vmcnt(0)
	v_cmp_ne_u32_e32 vcc, s38, v37
	v_cmp_ne_u32_e64 s[2:3], s38, v39
	s_or_b64 vcc, vcc, s[2:3]
	s_cbranch_vccz .Lsp_got
	s_add_i32 s39, s39, 1
	s_cmp_lt_u32 s39, 0x4000
	s_cbranch_scc0 .Lsp_got
	s_sleep 2
	s_branch .Lsp_poll
.Lsp_got:
	ds_read_b32 v0, v205
	s_waitcnt vmcnt(1) lgkmcnt(0)
	v_add_f32_e32 v0, v0, v36
	v_add_f32_e32 v4, v26, v0
	v_add_u32_e32 v0, v24, v206
	v_ashrrev_i32_e32 v1, 31, v0
	v_lshl_add_u64 v[2:3], v[0:1], 2, s[92:93]
	v_lshl_add_u64 v[0:1], v[0:1], 1, s[56:57]
	global_store_dword v[2:3], v4, off
	v_cvt_pk_bf16_f32 v2, v4, v33
	global_store_short v[0:1], v2, off
	v_and_b32_e32 v0, 64, v216
	v_add_u32_e32 v6, 64, v0
	v_xor_b32_e32 v0, 1, v216
	v_cmp_lt_i32_e32 vcc, v0, v6
	v_mul_f32_e32 v1, v4, v4
	s_nop 0
	v_cndmask_b32_e32 v0, v216, v0, vcc
	v_lshlrev_b32_e32 v0, 2, v0
	ds_bpermute_b32 v2, v0, v1
	v_xor_b32_e32 v1, 2, v216
	v_cmp_lt_i32_e32 vcc, v1, v6
	s_waitcnt lgkmcnt(0)
	v_fmac_f32_e32 v2, v4, v4
	v_cndmask_b32_e32 v1, v216, v1, vcc
	v_lshlrev_b32_e32 v1, 2, v1
	s_waitcnt lgkmcnt(0)
	s_nop 1
	v_add_f32_dpp v3, v2, v2 quad_perm:[2,3,0,1] row_mask:0xf bank_mask:0xf
	v_xor_b32_e32 v2, 4, v216
	v_cmp_lt_i32_e32 vcc, v2, v6
	s_nop 1
	v_cndmask_b32_e32 v2, v216, v2, vcc
	v_lshlrev_b32_e32 v2, 2, v2
	s_waitcnt lgkmcnt(0)
	s_nop 1
	v_add_f32_dpp v4, v3, v3 row_half_mirror row_mask:0xf bank_mask:0xf
	v_xor_b32_e32 v3, 8, v216
	v_cmp_lt_i32_e32 vcc, v3, v6
	s_nop 1
	v_cndmask_b32_e32 v3, v216, v3, vcc
	v_lshlrev_b32_e32 v3, 2, v3
	s_waitcnt lgkmcnt(0)
	s_nop 1
	v_add_f32_dpp v5, v4, v4 row_mirror row_mask:0xf bank_mask:0xf
	v_xor_b32_e32 v4, 16, v216
	v_cmp_lt_i32_e32 vcc, v4, v6
	s_nop 1
	v_cndmask_b32_e32 v4, v216, v4, vcc
	v_lshlrev_b32_e32 v4, 2, v4
	v_mov_b32_e32 v6, v5
	s_nop 1
	v_permlane16_swap_b32_e32 v6, v5
	s_and_saveexec_b64 s[2:3], s[90:91]
	s_cbranch_execz .LBB0_2760
	s_waitcnt lgkmcnt(0)
	v_add_f32_e32 v5, v5, v6
	v_mul_f32_e32 v5, 0x4b800000, v5
	v_trunc_f32_e32 v5, v5
	v_mul_f32_e32 v6, 0x2f800000, v5
	v_floor_f32_e32 v7, v6
	v_fmac_f32_e32 v5, 0xcf800000, v7
	v_cvt_u32_f32_e32 v6, v5
	v_cvt_u32_f32_e32 v7, v7
	global_atomic_add_x2 v[166:167], v[6:7], off
.LBB0_2760:
	s_or_b64 exec, exec, s[2:3]
	v_add_u32_e32 v5, v70, v208
	ds_read_b32 v5, v5
	s_waitcnt vmcnt(2) lgkmcnt(0)
	v_add_f32_e32 v5, v5, v38
	v_add_f32_e32 v5, v25, v5
	v_mul_f32_e32 v6, v5, v5
	ds_bpermute_b32 v0, v0, v6
	s_waitcnt lgkmcnt(0)
	v_fmac_f32_e32 v0, v5, v5
	s_waitcnt lgkmcnt(0)
	s_nop 1
	v_add_f32_dpp v0, v0, v0 quad_perm:[2,3,0,1] row_mask:0xf bank_mask:0xf
	v_add_u32_e32 v2, v24, v207
	s_waitcnt lgkmcnt(0)
	s_nop 1
	v_add_f32_dpp v0, v0, v0 row_half_mirror row_mask:0xf bank_mask:0xf
	v_ashrrev_i32_e32 v3, 31, v2
	v_lshl_add_u64 v[6:7], v[2:3], 2, s[92:93]
	v_lshl_add_u64 v[2:3], v[2:3], 1, s[56:57]
	global_store_dword v[6:7], v5, off
	s_waitcnt lgkmcnt(0)
	s_nop 1
	v_add_f32_dpp v0, v0, v0 row_mirror row_mask:0xf bank_mask:0xf
	v_mov_b32_e32 v1, v0
	s_nop 1
	v_permlane16_swap_b32_e32 v1, v0
	v_cvt_pk_bf16_f32 v4, v5, v33
	global_store_short v[2:3], v4, off
	s_and_saveexec_b64 s[2:3], s[90:91]
	s_cbranch_execz .LBB0_2754
	s_waitcnt lgkmcnt(0)
	v_add_f32_e32 v0, v0, v1
	v_mul_f32_e32 v0, 0x4b800000, v0
	v_trunc_f32_e32 v0, v0
	v_mul_f32_e32 v1, 0x2f800000, v0
	v_floor_f32_e32 v1, v1
	v_fmac_f32_e32 v0, 0xcf800000, v1
	v_cvt_u32_f32_e32 v0, v0
	v_cvt_u32_f32_e32 v1, v1
	global_atomic_add_x2 v[168:169], v[0:1], off
	s_branch .LBB0_2754
.Lsp_hi:
	ds_read_b32 v36, v205
	v_add_u32_e32 v38, v70, v208
	ds_read_b32 v38, v38
	v_mov_b32_e32 v37, s38
	v_mov_b32_e32 v39, s38
	s_waitcnt lgkmcnt(0)
	global_store_dwordx2 v[34:35], v[36:37], off sc1
	global_store_dwordx2 v[34:35], v[38:39], off offset:8 sc1
	s_mov_b64 s[2:3], exec
	s_branch .LBB0_2754

	.amdhsa_kernel _Z8yoco_fwd4Args
		.amdhsa_group_segment_fixed_size 0
		.amdhsa_private_segment_fixed_size 0
		.amdhsa_kernarg_size 480
		.amdhsa_user_sgpr_count 2
		.amdhsa_user_sgpr_dispatch_ptr 0
		.amdhsa_user_sgpr_queue_ptr 0
		.amdhsa_user_sgpr_kernarg_segment_ptr 1
		.amdhsa_user_sgpr_dispatch_id 0
		.amdhsa_user_sgpr_kernarg_preload_length 0
		.amdhsa_user_sgpr_kernarg_preload_offset 0
		.amdhsa_user_sgpr_private_segment_size 0
		.amdhsa_uses_dynamic_stack 0
		.amdhsa_enable_private_segment 0
		.amdhsa_system_sgpr_workgroup_id_x 1
		.amdhsa_system_sgpr_workgroup_id_y 0
		.amdhsa_system_sgpr_workgroup_id_z 0
		.amdhsa_system_sgpr_workgroup_info 0
		.amdhsa_system_vgpr_workitem_id 0
		.amdhsa_next_free_vgpr 256
		.amdhsa_next_free_sgpr 102
		.amdhsa_accum_offset 256
		.amdhsa_reserve_vcc 1
		.amdhsa_float_round_mode_32 0
		.amdhsa_float_round_mode_16_64 0
		.amdhsa_float_denorm_mode_32 3
		.amdhsa_float_denorm_mode_16_64 3
		.amdhsa_dx10_clamp 1
		.amdhsa_ieee_mode 1
		.amdhsa_fp16_overflow 0
		.amdhsa_tg_split 0
		.amdhsa_exception_fp_ieee_invalid_op 0
		.amdhsa_exception_fp_denorm_src 0
		.amdhsa_exception_fp_ieee_div_zero 0
		.amdhsa_exception_fp_ieee_overflow 0
		.amdhsa_exception_fp_ieee_underflow 0
		.amdhsa_exception_fp_ieee_inexact 0
		.amdhsa_exception_int_div_zero 0
	.end_amdhsa_kernel

amdhsa.kernels:
  - .agpr_count:     0
    .args:
      - .offset:         0
        .size:           224
        .value_kind:     by_value
      - .offset:         224
        .size:           4
        .value_kind:     hidden_block_count_x
      - .offset:         228
        .size:           4
        .value_kind:     hidden_block_count_y
      - .offset:         232
        .size:           4
        .value_kind:     hidden_block_count_z
      - .offset:         236
        .size:           2
        .value_kind:     hidden_group_size_x
      - .offset:         238
        .size:           2
        .value_kind:     hidden_group_size_y
      - .offset:         240
        .size:           2
        .value_kind:     hidden_group_size_z
      - .offset:         242
        .size:           2
        .value_kind:     hidden_remainder_x
      - .offset:         244
        .size:           2
        .value_kind:     hidden_remainder_y
      - .offset:         246
        .size:           2
        .value_kind:     hidden_remainder_z
      - .offset:         264
        .size:           8
        .value_kind:     hidden_global_offset_x
      - .offset:         272
        .size:           8
        .value_kind:     hidden_global_offset_y
      - .offset:         280
        .size:           8
        .value_kind:     hidden_global_offset_z
      - .offset:         288
        .size:           2
        .value_kind:     hidden_grid_dims
      - .offset:         344
        .size:           4
        .value_kind:     hidden_dynamic_lds_size
    .group_segment_fixed_size: 0
    .kernarg_segment_align: 8
    .kernarg_segment_size: 480
    .language:       OpenCL C
    .language_version:
      - 2
      - 0
    .max_flat_workgroup_size: 512
    .name:           _Z8yoco_fwd4Args
    .private_segment_fixed_size: 0
    .sgpr_count:     108
    .sgpr_spill_count: 398
    .symbol:         _Z8yoco_fwd4Args.kd
    .uniform_work_group_size: 1
    .uses_dynamic_stack: false
    .vgpr_count:     256
    .vgpr_spill_count: 0
    .wavefront_size: 64
